# P4->P6 and P6->next seams: the 1024 filler items go to every second wave of all 256 workgroups (4 per CU) instead of 8 per CU on workgroups 0..127
# baseline (speedup 1.0000x reference)
; #define FILL_SEAM(k, lo_, hi_, lo2_, hi2_) do { if (IN(k) && IN((k) + 1)) { if (l == 0 && DEPTH == 2) { xcd_barrier_arrive(xbar); CONVERT_ITEMS(I_L + (lo_), I_L + (hi_)); \
;         if ((hi2_) > (lo2_)) CONVERT_ITEMS(I_L + (lo2_), I_L + (hi2_)); xcd_barrier_wait(xbar); } else xcd_barrier(xbar); } } while (0)
; __global__ void __launch_bounds__(512, 2) mk_fwd(Args args) {
;     ...
;         FILL_SEAM(p1 + 4, I_IN, I_IN + I_O, 0, 0);
.LBB0_1239:
	s_or_b64 exec, exec, s[0:1]
	v_mov_b32_e32 v0, v252
	v_readlane_b32 s3, v254, 44
	v_readfirstlane_b32 s0, v0
	s_ashr_i32 s2, s0, 6
	s_add_i32 s24, s3, s2
	s_cmpk_lg_i32 s86, 0x100
	s_cbranch_scc1 .Lspread_done_44
	s_lshl_b32 s24, s96, 2
	s_lshr_b32 s3, s2, 1
	s_add_i32 s24, s24, s3
	s_addk_i32 s24, 0x2680
	s_bitcmp1_b32 s2, 0
	s_cselect_b32 s24, 0x7000, s24
.Lspread_done_44:
	s_mov_b64 s[0:1], s[20:21]
	s_cmpk_gt_i32 s24, 0x2a7f
	s_cbranch_scc1 .LBB0_1288
	s_add_u32 s25, s0, 0x200000
	s_addc_u32 s26, s1, 0
	s_add_u32 s27, s0, 0x3e00000
	s_addc_u32 s36, s1, 0
	s_add_u32 s37, s0, 0x4e00000
	s_addc_u32 s38, s1, 0
	s_add_u32 s39, s0, 0x5e00000
	s_addc_u32 s40, s1, 0
	s_add_u32 s41, s0, 0x10000
	s_addc_u32 s42, s1, 0
	v_and_b32_e32 v2, 63, v0
	v_bfe_u32 v69, v0, 4, 2
	v_bfe_u32 v80, v0, 3, 3
	v_lshlrev_b32_e32 v0, 3, v0
	s_add_u32 s43, s0, 0x14000
	s_mulk_i32 s2, 0x4100
	v_and_b32_e32 v70, 56, v0
	s_addc_u32 s44, s1, 0
	s_add_i32 s0, s2, 0
	v_lshlrev_b32_e32 v168, 2, v2
	v_mul_u32_u24_e32 v0, 0x104, v70
	v_lshlrev_b32_e32 v3, 2, v80
	v_and_b32_e32 v68, 60, v168
	v_add3_u32 v81, s0, v0, v3
	v_or_b32_e32 v0, 4, v69
	v_lshl_add_u32 v1, v68, 2, s0
	s_movk_i32 s1, 0x104
	v_mul_u32_u24_e32 v0, 0x104, v0
	v_mad_u32_u24 v71, v69, s1, v1
	v_or_b32_e32 v82, 8, v80
	v_or_b32_e32 v83, 16, v80
	v_or_b32_e32 v84, 24, v80
	v_or_b32_e32 v85, 32, v80
	v_or_b32_e32 v86, 40, v80
	v_or_b32_e32 v87, 48, v80
	v_or_b32_e32 v88, 56, v80
	v_add_u32_e32 v89, s0, v168
	v_lshl_add_u64 v[72:73], s[16:17], 0, v[168:169]
	v_lshlrev_b32_e32 v74, 2, v2
	v_add_u32_e32 v90, v1, v0
	s_branch .LBB0_1242

; #define FILL_SEAM(k, lo_, hi_, lo2_, hi2_) do { if (IN(k) && IN((k) + 1)) { if (l == 0 && DEPTH == 2) { xcd_barrier_arrive(xbar); CONVERT_ITEMS(I_L + (lo_), I_L + (hi_)); \
;         if ((hi2_) > (lo2_)) CONVERT_ITEMS(I_L + (lo2_), I_L + (hi2_)); xcd_barrier_wait(xbar); } else xcd_barrier(xbar); } } while (0)
; __global__ void __launch_bounds__(512, 2) mk_fwd(Args args) {
;     ...
;         if (l + 1 < DEPTH) FILL_SEAM(p1 + 5, I_IN + I_O, I_IN + 2 * I_O, 0, 0);
.LBB0_1408:
	s_or_b64 exec, exec, s[0:1]
	v_mov_b32_e32 v0, v252
	v_readlane_b32 s3, v254, 47
	v_readfirstlane_b32 s0, v0
	s_ashr_i32 s2, s0, 6
	s_add_i32 s24, s3, s2
	s_cmpk_lg_i32 s86, 0x100
	s_cbranch_scc1 .Lspread_done_47
	s_lshl_b32 s24, s96, 2
	s_lshr_b32 s3, s2, 1
	s_add_i32 s24, s24, s3
	s_addk_i32 s24, 0x2a80
	s_bitcmp1_b32 s2, 0
	s_cselect_b32 s24, 0x7000, s24
.Lspread_done_47:
	s_mov_b64 s[0:1], s[20:21]
	s_cmpk_gt_i32 s24, 0x2e7f
	s_cbranch_scc1 .LBB0_1457
	s_add_u32 s25, s0, 0x200000
	s_addc_u32 s26, s1, 0
	s_add_u32 s27, s0, 0x3e00000
	s_addc_u32 s28, s1, 0
	s_add_u32 s36, s0, 0x4e00000
	s_addc_u32 s37, s1, 0
	s_add_u32 s38, s0, 0x5e00000
	s_addc_u32 s39, s1, 0
	s_add_u32 s40, s0, 0x10000
	s_addc_u32 s41, s1, 0
	v_and_b32_e32 v2, 63, v0
	v_bfe_u32 v69, v0, 4, 2
	v_bfe_u32 v80, v0, 3, 3
	v_lshlrev_b32_e32 v0, 3, v0
	s_add_u32 s42, s0, 0x14000
	s_mulk_i32 s2, 0x4100
	v_and_b32_e32 v70, 56, v0
	s_addc_u32 s43, s1, 0
	s_add_i32 s0, s2, 0
	v_lshlrev_b32_e32 v168, 2, v2
	v_mul_u32_u24_e32 v0, 0x104, v70
	v_lshlrev_b32_e32 v3, 2, v80
	v_and_b32_e32 v68, 60, v168
	v_add3_u32 v81, s0, v0, v3
	v_or_b32_e32 v0, 4, v69
	v_lshl_add_u32 v1, v68, 2, s0
	s_movk_i32 s1, 0x104
	v_mul_u32_u24_e32 v0, 0x104, v0
	v_mad_u32_u24 v71, v69, s1, v1
	v_or_b32_e32 v82, 8, v80
	v_or_b32_e32 v83, 16, v80
	v_or_b32_e32 v84, 24, v80
	v_or_b32_e32 v85, 32, v80
	v_or_b32_e32 v86, 40, v80
	v_or_b32_e32 v87, 48, v80
	v_or_b32_e32 v88, 56, v80
	v_add_u32_e32 v89, s0, v168
	v_lshl_add_u64 v[72:73], s[16:17], 0, v[168:169]
	v_lshlrev_b32_e32 v74, 2, v2
	v_add_u32_e32 v90, v1, v0
	s_branch .LBB0_1411
